# attnC: running max folded into the QK accumulator (MFMA accumulates onto a -m register block, no per-element subtraction), K/V tiles by LDS-DMA in a 3-slot ring
# speedup vs baseline: 1.0273x; 1.0273x over previous
; #define LAS __attribute__((address_space(3)))
; __device__ __forceinline__ float fexp2(float x) { return __builtin_amdgcn_exp2f(x); }
; template <bool KLDS>
; __device__ __forceinline__ void attn_step(const bf16x8 (&kf)[4], LAS const unsigned char* kb, const bf16x8 (&vf)[2][2], const bf16x8 (&qf)[4], f32x16& o0, f32x16& o1, float& m, float& l, int lane, int maskmode) {
;     ...
;     for (int s = 0; s < 4; ++s) {
;         if (KLDS) { const int pc = (2 * s + h) ^ ((ql >> 1) & 7); const bf16x8 k1 = *(const LAS bf16x8*)(kb + ql * 128 + pc * 16); S = __builtin_amdgcn_mfma_f32_32x32x16_bf16(k1, qf[s], S, 0, 0, 0); }
;         else S = __builtin_amdgcn_mfma_f32_32x32x16_bf16(kf[s], qf[s], S, 0, 0, 0);
;     }
;     if (maskmode) {
; #pragma unroll
;         for (int i = 0; i < 16; ++i) { const int kr = (i & 3) + 8 * (i >> 2) + 4 * h; const bool ok = (maskmode == 1) ? (kr >= ql) : (kr <= ql); S[i] = ok ? S[i] : -1e30f; }
;     }
;     float tm = S[0];
; #pragma unroll
;     for (int i = 1; i < 16; ++i) tm = fmaxf(tm, S[i]);
;     tm = fmaxf(tm, __shfl_xor(tm, 32));
;     const float mn = fmaxf(m, tm), al = fexp2(m - mn); m = mn;
;     float ps = 0.f;
; #pragma unroll
;     for (int i = 0; i < 16; ++i) { S[i] = fexp2(S[i] - mn); ps += S[i]; }
;     l = l * al + ps;
; #pragma unroll
;     for (int i = 0; i < 16; ++i) { o0[i] *= al; o1[i] *= al; }
; __device__ __forceinline__ void attnC_unit(const Args& a, int unit, LAS unsigned char* lds) {
;     ...
;     for (int kt = 0; kt < 32; ++kt) {
;         LAS unsigned char* cur = lds + (kt & 1) * 16384;
;         LAS unsigned char* nxt = lds + ((kt + 1) & 1) * 16384;
;         if (kt + 1 < 32) { *(LAS u32x4*)(nxt + kwo) = rk; *(LAS u32x4*)(nxt + vwo) = rv; }
;         if (kt + 2 < 32) { rk = *(const u32x4*)(kg + (size_t)(kt + 2) * TSTEP); rv = *(const u32x4*)(vg + (size_t)(kt + 2) * TSTEP); }
; #pragma unroll
;         for (int j = 0; j < 2; ++j) {
;             bf16x8 kf[4], vf[2][2];
;             load_kf(cur + j * 4096, kf, lane); load_vf(cur + 8192 + j * 4096, vf, lane);
; #pragma unroll
;             for (int e = 0; e < 2; ++e) attn_step<false>(kf, cur, vf, qf[e], o0[e], o1[e], m[e], l[e], lane, 0);
.LaN_entry:
	s_waitcnt vmcnt(0)
	v_add_u32_e32 v142, 0x4000, v250
	v_add_u32_e32 v143, 0x4000, v251
	ds_write_b128 v142, v[112:115]
	ds_write_b128 v143, v[116:119] offset:8192
	v_and_b32_e32 v142, 7, v225
	v_bfe_u32 v143, v225, 4, 3
	v_xor_b32_e32 v143, v143, v142
	v_sub_u32_e32 v143, v143, v142
	v_lshlrev_b32_e32 v143, 4, v143
	v_add_u32_e32 v143, 0xffffff00, v143
	v_ashrrev_i32_e32 v144, 31, v143
	v_add_co_u32_e32 v198, vcc, v180, v143
	s_nop 0
	v_addc_co_u32_e32 v199, vcc, v181, v144, vcc
	v_readfirstlane_b32 s28, v225
	s_lshl_b32 s28, s28, 4
	s_mov_b32 s29, 0
	s_movk_i32 s30, 0x4000
	s_mov_b32 s31, 0x8000
	s_mov_b32 s3, 0
	v_mov_b32_e32 v182, 0
	v_mov_b32_e32 v183, 0
	v_mov_b32_e32 v184, 0
	v_mov_b32_e32 v185, 0
	v_mov_b32_e32 v186, 0
	v_mov_b32_e32 v187, 0
	v_mov_b32_e32 v188, 0
	v_mov_b32_e32 v189, 0
	v_mov_b32_e32 v190, 0
	v_mov_b32_e32 v191, 0
	v_mov_b32_e32 v192, 0
	v_mov_b32_e32 v193, 0
	v_mov_b32_e32 v194, 0
	v_mov_b32_e32 v195, 0
	v_mov_b32_e32 v196, 0
	v_mov_b32_e32 v197, 0
	v_mov_b32_e32 v120, 0
	v_mov_b32_e32 v121, 0
	v_mov_b32_e32 v122, 0
	v_mov_b32_e32 v123, 0
	v_mov_b32_e32 v124, 0
	v_mov_b32_e32 v125, 0
	v_mov_b32_e32 v126, 0
	v_mov_b32_e32 v127, 0
	v_mov_b32_e32 v128, 0
	v_mov_b32_e32 v129, 0
	v_mov_b32_e32 v130, 0
	v_mov_b32_e32 v131, 0
	v_mov_b32_e32 v132, 0
	v_mov_b32_e32 v133, 0
	v_mov_b32_e32 v134, 0
	v_mov_b32_e32 v135, 0
	s_waitcnt lgkmcnt(0)
.LaN_loop:
	s_cmp_lt_u32 s3, 30
	s_cbranch_scc1 .LaN_w2
	s_waitcnt vmcnt(0)
	s_branch .LaN_wd
.LaN_w2:
	s_waitcnt vmcnt(2)
.LaN_wd:
	s_barrier
	s_cmp_lt_u32 s3, 30
	s_cbranch_scc0 .LaN_nd
	s_add_i32 s33, s31, s28
	s_mov_b32 m0, s33
	s_nop 0
	global_load_lds_dwordx4 v[198:199], off
	s_add_i32 m0, s33, 0x2000
	s_nop 0
	global_load_lds_dwordx4 v[180:181], off
	v_lshl_add_u64 v[198:199], v[198:199], 0, s[18:19]
	v_lshl_add_u64 v[180:181], v[180:181], 0, s[18:19]
.LaN_nd:
	v_add3_u32 v137, s29, v157, v156
	v_add3_u32 v142, s29, v252, v231
	v_add3_u32 v143, s29, v252, v239
	v_add3_u32 v144, s29, v252, v232
	v_add3_u32 v145, s29, v252, v241
	s_mov_b32 s9, 0x41000000
	s_cmp_eq_u32 s3, 0
	s_cselect_b32 s9, 0xff800000, s9
	ds_read_b128 v[112:115], v142
	ds_read_b128 v[116:119], v143
	ds_read_b128 v[216:219], v144
	ds_read_b128 v[220:223], v145
	ds_read_b64_tr_b16 v[146:147], v137 offset:8192
	ds_read_b64_tr_b16 v[148:149], v137 offset:9216
	ds_read_b64_tr_b16 v[204:205], v137 offset:8256
	ds_read_b64_tr_b16 v[206:207], v137 offset:9280
	ds_read_b64_tr_b16 v[208:209], v137 offset:10240
	ds_read_b64_tr_b16 v[210:211], v137 offset:11264
	ds_read_b64_tr_b16 v[212:213], v137 offset:10304
	ds_read_b64_tr_b16 v[214:215], v137 offset:11328
	s_waitcnt lgkmcnt(11)
	v_mfma_f32_32x32x16_bf16 v[64:79], v[112:115], v[80:83], v[182:197]
	v_mfma_f32_32x32x16_bf16 v[158:173], v[112:115], v[96:99], v[120:135]
	s_waitcnt lgkmcnt(10)
	v_mfma_f32_32x32x16_bf16 v[64:79], v[116:119], v[84:87], v[64:79]
	v_mfma_f32_32x32x16_bf16 v[158:173], v[116:119], v[100:103], v[158:173]
	s_waitcnt lgkmcnt(9)
	v_mfma_f32_32x32x16_bf16 v[64:79], v[216:219], v[88:91], v[64:79]
	v_mfma_f32_32x32x16_bf16 v[158:173], v[216:219], v[104:107], v[158:173]
	s_waitcnt lgkmcnt(8)
	v_mfma_f32_32x32x16_bf16 v[64:79], v[220:223], v[92:95], v[64:79]
	v_mfma_f32_32x32x16_bf16 v[158:173], v[220:223], v[108:111], v[158:173]
	s_nop 10
	v_max3_f32 v152, v64, v65, v66
	v_max3_f32 v150, v158, v159, v160
	v_max3_f32 v152, v152, v67, v68
	v_max3_f32 v150, v150, v161, v162
	v_max3_f32 v152, v152, v69, v70
	v_max3_f32 v150, v150, v163, v164
	v_max3_f32 v152, v152, v71, v72
	v_max3_f32 v150, v150, v165, v166
	v_max3_f32 v152, v152, v73, v74
	v_max3_f32 v150, v150, v167, v168
	v_max3_f32 v152, v152, v75, v76
	v_max3_f32 v150, v150, v169, v170
	v_max3_f32 v152, v152, v77, v78
	v_max3_f32 v150, v150, v171, v172
	v_max_f32_e32 v152, v152, v79
	v_max_f32_e32 v150, v150, v173
	v_mov_b32_e32 v153, v152
	v_mov_b32_e32 v151, v150
	s_nop 1
	s_nop 1
	v_permlane32_swap_b32_e32 v153, v152
	v_permlane32_swap_b32_e32 v151, v150
	v_max_f32_e32 v152, v152, v153
	v_max_f32_e32 v150, v150, v151
	v_cmp_lt_f32_e64 s[10:11], s9, v152
	v_cmp_lt_f32_e64 s[4:5], s9, v150
	s_nop 0
	s_or_b64 vcc, s[10:11], s[4:5]
	s_cbranch_vccz .LaN_fj0
	s_nop 15
	s_nop 15
	v_cndmask_b32_e64 v154, 0, v152, s[10:11]
	v_sub_f32_e32 v64, v64, v154
	v_sub_f32_e32 v65, v65, v154
	v_sub_f32_e32 v66, v66, v154
	v_sub_f32_e32 v67, v67, v154
	v_sub_f32_e32 v68, v68, v154
	v_sub_f32_e32 v69, v69, v154
	v_sub_f32_e32 v70, v70, v154
	v_sub_f32_e32 v71, v71, v154
	v_sub_f32_e32 v72, v72, v154
	v_sub_f32_e32 v73, v73, v154
	v_sub_f32_e32 v74, v74, v154
	v_sub_f32_e32 v75, v75, v154
	v_sub_f32_e32 v76, v76, v154
	v_sub_f32_e32 v77, v77, v154
	v_sub_f32_e32 v78, v78, v154
	v_sub_f32_e32 v79, v79, v154
	v_sub_f32_e32 v182, v182, v154
	v_sub_f32_e32 v183, v183, v154
	v_sub_f32_e32 v184, v184, v154
	v_sub_f32_e32 v185, v185, v154
	v_sub_f32_e32 v186, v186, v154
	v_sub_f32_e32 v187, v187, v154
	v_sub_f32_e32 v188, v188, v154
	v_sub_f32_e32 v189, v189, v154
	v_sub_f32_e32 v190, v190, v154
	v_sub_f32_e32 v191, v191, v154
	v_sub_f32_e32 v192, v192, v154
	v_sub_f32_e32 v193, v193, v154
	v_sub_f32_e32 v194, v194, v154
	v_sub_f32_e32 v195, v195, v154
	v_sub_f32_e32 v196, v196, v154
	v_sub_f32_e32 v197, v197, v154
	s_cmp_eq_u32 s3, 0
	s_cbranch_scc1 .LaN_nrj00
	v_sub_f32_e32 v153, 0, v154
	v_exp_f32_e32 v154, v153
	s_nop 0
	v_mul_f32_e32 v179, v179, v154
	v_pk_mul_f32 v[48:49], v[48:49], v[154:155] op_sel_hi:[1,0]
	v_pk_mul_f32 v[50:51], v[50:51], v[154:155] op_sel_hi:[1,0]
	v_pk_mul_f32 v[52:53], v[52:53], v[154:155] op_sel_hi:[1,0]
	v_pk_mul_f32 v[54:55], v[54:55], v[154:155] op_sel_hi:[1,0]
	v_pk_mul_f32 v[56:57], v[56:57], v[154:155] op_sel_hi:[1,0]
	v_pk_mul_f32 v[58:59], v[58:59], v[154:155] op_sel_hi:[1,0]
	v_pk_mul_f32 v[60:61], v[60:61], v[154:155] op_sel_hi:[1,0]
	v_pk_mul_f32 v[62:63], v[62:63], v[154:155] op_sel_hi:[1,0]
	v_pk_mul_f32 v[32:33], v[32:33], v[154:155] op_sel_hi:[1,0]
	v_pk_mul_f32 v[34:35], v[34:35], v[154:155] op_sel_hi:[1,0]
	v_pk_mul_f32 v[36:37], v[36:37], v[154:155] op_sel_hi:[1,0]
	v_pk_mul_f32 v[38:39], v[38:39], v[154:155] op_sel_hi:[1,0]
	v_pk_mul_f32 v[40:41], v[40:41], v[154:155] op_sel_hi:[1,0]
	v_pk_mul_f32 v[42:43], v[42:43], v[154:155] op_sel_hi:[1,0]
	v_pk_mul_f32 v[44:45], v[44:45], v[154:155] op_sel_hi:[1,0]
	v_pk_mul_f32 v[46:47], v[46:47], v[154:155] op_sel_hi:[1,0]
; __device__ __forceinline__ unsigned pk2n(float lo, float hi) { const f32x2v v = {lo, hi}; const bf16v2 b = __builtin_convertvector(v, bf16v2); return __builtin_bit_cast(unsigned, b); }
; __device__ __forceinline__ float fexp2(float x) { return __builtin_amdgcn_exp2f(x); }
; template <bool KLDS>
; __device__ __forceinline__ void attn_step(const bf16x8 (&kf)[4], LAS const unsigned char* kb, const bf16x8 (&vf)[2][2], const bf16x8 (&qf)[4], f32x16& o0, f32x16& o1, float& m, float& l, int lane, int maskmode) {
;     ...
;     const float mn = fmaxf(m, tm), al = fexp2(m - mn); m = mn;
;     float ps = 0.f;
; #pragma unroll
;     for (int i = 0; i < 16; ++i) { S[i] = fexp2(S[i] - mn); ps += S[i]; }
;     l = l * al + ps;
; #pragma unroll
;     for (int i = 0; i < 16; ++i) { o0[i] *= al; o1[i] *= al; }
;     bf16x8 pf[2];
; #pragma unroll
;     for (int s2 = 0; s2 < 2; ++s2) {
;         u32x4 w; w.x = pk2n(S[8 * s2 + 0], S[8 * s2 + 1]); w.y = pk2n(S[8 * s2 + 2], S[8 * s2 + 3]); w.z = pk2n(S[8 * s2 + 4], S[8 * s2 + 5]); w.w = pk2n(S[8 * s2 + 6], S[8 * s2 + 7]);
;         pf[s2] = __builtin_bit_cast(bf16x8, w);
;     }
; #pragma unroll
;     for (int s2 = 0; s2 < 2; ++s2) {
;         o0 = __builtin_amdgcn_mfma_f32_32x32x16_bf16(vf[s2][0], pf[s2], o0, 0, 0, 0);
;         o1 = __builtin_amdgcn_mfma_f32_32x32x16_bf16(vf[s2][1], pf[s2], o1, 0, 0, 0);
;     }
.LaN_nrj00:
	v_cndmask_b32_e64 v174, 0, v150, s[4:5]
	v_sub_f32_e32 v158, v158, v174
	v_sub_f32_e32 v159, v159, v174
	v_sub_f32_e32 v160, v160, v174
	v_sub_f32_e32 v161, v161, v174
	v_sub_f32_e32 v162, v162, v174
	v_sub_f32_e32 v163, v163, v174
	v_sub_f32_e32 v164, v164, v174
	v_sub_f32_e32 v165, v165, v174
	v_sub_f32_e32 v166, v166, v174
	v_sub_f32_e32 v167, v167, v174
	v_sub_f32_e32 v168, v168, v174
	v_sub_f32_e32 v169, v169, v174
	v_sub_f32_e32 v170, v170, v174
	v_sub_f32_e32 v171, v171, v174
	v_sub_f32_e32 v172, v172, v174
	v_sub_f32_e32 v173, v173, v174
	v_sub_f32_e32 v120, v120, v174
	v_sub_f32_e32 v121, v121, v174
	v_sub_f32_e32 v122, v122, v174
	v_sub_f32_e32 v123, v123, v174
	v_sub_f32_e32 v124, v124, v174
	v_sub_f32_e32 v125, v125, v174
	v_sub_f32_e32 v126, v126, v174
	v_sub_f32_e32 v127, v127, v174
	v_sub_f32_e32 v128, v128, v174
	v_sub_f32_e32 v129, v129, v174
	v_sub_f32_e32 v130, v130, v174
	v_sub_f32_e32 v131, v131, v174
	v_sub_f32_e32 v132, v132, v174
	v_sub_f32_e32 v133, v133, v174
	v_sub_f32_e32 v134, v134, v174
	v_sub_f32_e32 v135, v135, v174
	s_cmp_eq_u32 s3, 0
	s_cbranch_scc1 .LaN_nrj01
	v_sub_f32_e32 v151, 0, v174
	v_exp_f32_e32 v174, v151
	s_nop 0
	v_mul_f32_e32 v178, v178, v174
	v_pk_mul_f32 v[16:17], v[16:17], v[174:175] op_sel_hi:[1,0]
	v_pk_mul_f32 v[18:19], v[18:19], v[174:175] op_sel_hi:[1,0]
	v_pk_mul_f32 v[20:21], v[20:21], v[174:175] op_sel_hi:[1,0]
	v_pk_mul_f32 v[22:23], v[22:23], v[174:175] op_sel_hi:[1,0]
	v_pk_mul_f32 v[24:25], v[24:25], v[174:175] op_sel_hi:[1,0]
	v_pk_mul_f32 v[26:27], v[26:27], v[174:175] op_sel_hi:[1,0]
	v_pk_mul_f32 v[28:29], v[28:29], v[174:175] op_sel_hi:[1,0]
	v_pk_mul_f32 v[30:31], v[30:31], v[174:175] op_sel_hi:[1,0]
	v_pk_mul_f32 v[0:1], v[0:1], v[174:175] op_sel_hi:[1,0]
	v_pk_mul_f32 v[2:3], v[2:3], v[174:175] op_sel_hi:[1,0]
	v_pk_mul_f32 v[4:5], v[4:5], v[174:175] op_sel_hi:[1,0]
	v_pk_mul_f32 v[6:7], v[6:7], v[174:175] op_sel_hi:[1,0]
	v_pk_mul_f32 v[8:9], v[8:9], v[174:175] op_sel_hi:[1,0]
	v_pk_mul_f32 v[10:11], v[10:11], v[174:175] op_sel_hi:[1,0]
	v_pk_mul_f32 v[12:13], v[12:13], v[174:175] op_sel_hi:[1,0]
	v_pk_mul_f32 v[14:15], v[14:15], v[174:175] op_sel_hi:[1,0]
.LaN_nrj01:
.LaN_fj0:
	v_exp_f32_e32 v64, v64
	v_exp_f32_e32 v158, v158
	v_exp_f32_e32 v65, v65
	v_exp_f32_e32 v159, v159
	v_exp_f32_e32 v66, v66
	v_exp_f32_e32 v160, v160
	v_add_f32_e32 v138, v64, v65
	v_add_f32_e32 v140, v158, v159
	v_exp_f32_e32 v67, v67
	v_exp_f32_e32 v161, v161
	v_add_f32_e32 v139, v66, v67
	v_add_f32_e32 v141, v160, v161
	v_exp_f32_e32 v68, v68
	v_exp_f32_e32 v162, v162
	v_exp_f32_e32 v69, v69
	v_exp_f32_e32 v163, v163
	v_add_f32_e32 v139, v139, v68
	v_add_f32_e32 v141, v141, v162
	v_exp_f32_e32 v70, v70
	v_exp_f32_e32 v164, v164
	v_add_f32_e32 v138, v138, v69
	v_add_f32_e32 v140, v140, v163
	v_exp_f32_e32 v71, v71
	v_exp_f32_e32 v165, v165
	v_add_f32_e32 v139, v139, v70
	v_add_f32_e32 v141, v141, v164
	v_exp_f32_e32 v72, v72
	v_exp_f32_e32 v166, v166
	v_add_f32_e32 v138, v138, v71
	v_add_f32_e32 v140, v140, v165
	v_exp_f32_e32 v73, v73
	v_exp_f32_e32 v167, v167
	v_add_f32_e32 v139, v139, v72
	v_add_f32_e32 v141, v141, v166
	v_exp_f32_e32 v74, v74
	v_exp_f32_e32 v168, v168
	v_add_f32_e32 v138, v138, v73
	v_add_f32_e32 v140, v140, v167
	v_exp_f32_e32 v75, v75
	v_exp_f32_e32 v169, v169
	v_add_f32_e32 v139, v139, v74
	v_add_f32_e32 v141, v141, v168
	v_exp_f32_e32 v76, v76
	v_exp_f32_e32 v170, v170
	v_add_f32_e32 v138, v138, v75
	v_add_f32_e32 v140, v140, v169
	v_exp_f32_e32 v77, v77
	v_exp_f32_e32 v171, v171
	v_add_f32_e32 v139, v139, v76
	v_add_f32_e32 v141, v141, v170
	v_exp_f32_e32 v78, v78
	v_exp_f32_e32 v172, v172
	v_add_f32_e32 v138, v138, v77
	v_add_f32_e32 v140, v140, v171
	v_exp_f32_e32 v79, v79
	v_exp_f32_e32 v173, v173
	v_add_f32_e32 v139, v139, v78
	v_add_f32_e32 v141, v141, v172
	s_nop 0
	s_nop 0
	v_add_f32_e32 v139, v139, v79
	v_add_f32_e32 v141, v141, v173
	v_add_f32_e32 v138, v138, v139
	v_add_f32_e32 v140, v140, v141
	v_add_f32_e32 v179, v179, v138
	v_add_f32_e32 v178, v178, v140
	v_cvt_pk_bf16_f32 v64, v64, v65
	v_cvt_pk_bf16_f32 v158, v158, v159
	v_cvt_pk_bf16_f32 v65, v66, v67
	v_cvt_pk_bf16_f32 v159, v160, v161
	v_cvt_pk_bf16_f32 v66, v68, v69
	v_cvt_pk_bf16_f32 v160, v162, v163
	v_cvt_pk_bf16_f32 v67, v70, v71
	v_cvt_pk_bf16_f32 v161, v164, v165
	v_cvt_pk_bf16_f32 v68, v72, v73
	v_cvt_pk_bf16_f32 v162, v166, v167
	v_cvt_pk_bf16_f32 v69, v74, v75
	v_cvt_pk_bf16_f32 v163, v168, v169
	v_cvt_pk_bf16_f32 v70, v76, v77
	v_cvt_pk_bf16_f32 v164, v170, v171
	v_cvt_pk_bf16_f32 v71, v78, v79
	v_cvt_pk_bf16_f32 v165, v172, v173
	s_waitcnt lgkmcnt(0)
	v_mfma_f32_32x32x16_bf16 v[48:63], v[146:149], v[64:67], v[48:63]
	v_mfma_f32_32x32x16_bf16 v[16:31], v[146:149], v[158:161], v[16:31]
	v_mfma_f32_32x32x16_bf16 v[32:47], v[204:207], v[64:67], v[32:47]
	v_mfma_f32_32x32x16_bf16 v[0:15], v[204:207], v[158:161], v[0:15]
	v_mfma_f32_32x32x16_bf16 v[48:63], v[208:211], v[68:71], v[48:63]
	v_mfma_f32_32x32x16_bf16 v[16:31], v[208:211], v[162:165], v[16:31]
	v_mfma_f32_32x32x16_bf16 v[32:47], v[212:215], v[68:71], v[32:47]
	v_mfma_f32_32x32x16_bf16 v[0:15], v[212:215], v[162:165], v[0:15]
	s_mov_b32 s9, 0x41000000
	ds_read_b128 v[112:115], v142 offset:4096
	ds_read_b128 v[116:119], v143 offset:4096
	ds_read_b128 v[216:219], v144 offset:4096
	ds_read_b128 v[220:223], v145 offset:4096
	ds_read_b64_tr_b16 v[146:147], v137 offset:12288
	ds_read_b64_tr_b16 v[148:149], v137 offset:13312
	ds_read_b64_tr_b16 v[204:205], v137 offset:12352
	ds_read_b64_tr_b16 v[206:207], v137 offset:13376
	ds_read_b64_tr_b16 v[208:209], v137 offset:14336
	ds_read_b64_tr_b16 v[210:211], v137 offset:15360
	ds_read_b64_tr_b16 v[212:213], v137 offset:14400
	ds_read_b64_tr_b16 v[214:215], v137 offset:15424
	s_waitcnt lgkmcnt(11)
; #define LAS __attribute__((address_space(3)))
; __device__ __forceinline__ unsigned pk2n(float lo, float hi) { const f32x2v v = {lo, hi}; const bf16v2 b = __builtin_convertvector(v, bf16v2); return __builtin_bit_cast(unsigned, b); }
; __device__ __forceinline__ float fexp2(float x) { return __builtin_amdgcn_exp2f(x); }
; template <bool KLDS>
; __device__ __forceinline__ void attn_step(const bf16x8 (&kf)[4], LAS const unsigned char* kb, const bf16x8 (&vf)[2][2], const bf16x8 (&qf)[4], f32x16& o0, f32x16& o1, float& m, float& l, int lane, int maskmode) {
;     ...
;     for (int s = 0; s < 4; ++s) {
;         if (KLDS) { const int pc = (2 * s + h) ^ ((ql >> 1) & 7); const bf16x8 k1 = *(const LAS bf16x8*)(kb + ql * 128 + pc * 16); S = __builtin_amdgcn_mfma_f32_32x32x16_bf16(k1, qf[s], S, 0, 0, 0); }
;         else S = __builtin_amdgcn_mfma_f32_32x32x16_bf16(kf[s], qf[s], S, 0, 0, 0);
;     }
;     if (maskmode) {
; #pragma unroll
;         for (int i = 0; i < 16; ++i) { const int kr = (i & 3) + 8 * (i >> 2) + 4 * h; const bool ok = (maskmode == 1) ? (kr >= ql) : (kr <= ql); S[i] = ok ? S[i] : -1e30f; }
;     }
;     float tm = S[0];
; #pragma unroll
;     for (int i = 1; i < 16; ++i) tm = fmaxf(tm, S[i]);
;     tm = fmaxf(tm, __shfl_xor(tm, 32));
;     const float mn = fmaxf(m, tm), al = fexp2(m - mn); m = mn;
;     float ps = 0.f;
; #pragma unroll
;     for (int i = 0; i < 16; ++i) { S[i] = fexp2(S[i] - mn); ps += S[i]; }
;     l = l * al + ps;
; #pragma unroll
;     for (int i = 0; i < 16; ++i) { o0[i] *= al; o1[i] *= al; }
;     bf16x8 pf[2];
; #pragma unroll
;     for (int s2 = 0; s2 < 2; ++s2) {
;         u32x4 w; w.x = pk2n(S[8 * s2 + 0], S[8 * s2 + 1]); w.y = pk2n(S[8 * s2 + 2], S[8 * s2 + 3]); w.z = pk2n(S[8 * s2 + 4], S[8 * s2 + 5]); w.w = pk2n(S[8 * s2 + 6], S[8 * s2 + 7]);
;         pf[s2] = __builtin_bit_cast(bf16x8, w);
;     }
; #pragma unroll
;     for (int s2 = 0; s2 < 2; ++s2) {
;         o0 = __builtin_amdgcn_mfma_f32_32x32x16_bf16(vf[s2][0], pf[s2], o0, 0, 0, 0);
;         o1 = __builtin_amdgcn_mfma_f32_32x32x16_bf16(vf[s2][1], pf[s2], o1, 0, 0, 0);
;     }
	v_mfma_f32_32x32x16_bf16 v[64:79], v[112:115], v[80:83], v[182:197]
	v_mfma_f32_32x32x16_bf16 v[158:173], v[112:115], v[96:99], v[120:135]
	s_waitcnt lgkmcnt(10)
	v_mfma_f32_32x32x16_bf16 v[64:79], v[116:119], v[84:87], v[64:79]
	v_mfma_f32_32x32x16_bf16 v[158:173], v[116:119], v[100:103], v[158:173]
	s_waitcnt lgkmcnt(9)
	v_mfma_f32_32x32x16_bf16 v[64:79], v[216:219], v[88:91], v[64:79]
	v_mfma_f32_32x32x16_bf16 v[158:173], v[216:219], v[104:107], v[158:173]
	s_waitcnt lgkmcnt(8)
	v_mfma_f32_32x32x16_bf16 v[64:79], v[220:223], v[92:95], v[64:79]
	v_mfma_f32_32x32x16_bf16 v[158:173], v[220:223], v[108:111], v[158:173]
	s_nop 10
	v_max3_f32 v152, v64, v65, v66
	v_max3_f32 v150, v158, v159, v160
	v_max3_f32 v152, v152, v67, v68
	v_max3_f32 v150, v150, v161, v162
	v_max3_f32 v152, v152, v69, v70
	v_max3_f32 v150, v150, v163, v164
	v_max3_f32 v152, v152, v71, v72
	v_max3_f32 v150, v150, v165, v166
	v_max3_f32 v152, v152, v73, v74
	v_max3_f32 v150, v150, v167, v168
	v_max3_f32 v152, v152, v75, v76
	v_max3_f32 v150, v150, v169, v170
	v_max3_f32 v152, v152, v77, v78
	v_max3_f32 v150, v150, v171, v172
	v_max_f32_e32 v152, v152, v79
	v_max_f32_e32 v150, v150, v173
	v_mov_b32_e32 v153, v152
	v_mov_b32_e32 v151, v150
	s_nop 1
	s_nop 1
	v_permlane32_swap_b32_e32 v153, v152
	v_permlane32_swap_b32_e32 v151, v150
	v_max_f32_e32 v152, v152, v153
	v_max_f32_e32 v150, v150, v151
	v_cmp_lt_f32_e64 s[10:11], s9, v152
	v_cmp_lt_f32_e64 s[4:5], s9, v150
	s_nop 0
	s_or_b64 vcc, s[10:11], s[4:5]
	s_cbranch_vccz .LaN_fj1
	s_nop 15
	s_nop 15
	v_cndmask_b32_e64 v154, 0, v152, s[10:11]
	v_sub_f32_e32 v64, v64, v154
	v_sub_f32_e32 v65, v65, v154
	v_sub_f32_e32 v66, v66, v154
	v_sub_f32_e32 v67, v67, v154
	v_sub_f32_e32 v68, v68, v154
	v_sub_f32_e32 v69, v69, v154
	v_sub_f32_e32 v70, v70, v154
	v_sub_f32_e32 v71, v71, v154
	v_sub_f32_e32 v72, v72, v154
	v_sub_f32_e32 v73, v73, v154
	v_sub_f32_e32 v74, v74, v154
	v_sub_f32_e32 v75, v75, v154
	v_sub_f32_e32 v76, v76, v154
	v_sub_f32_e32 v77, v77, v154
	v_sub_f32_e32 v78, v78, v154
	v_sub_f32_e32 v79, v79, v154
	v_sub_f32_e32 v182, v182, v154
	v_sub_f32_e32 v183, v183, v154
	v_sub_f32_e32 v184, v184, v154
	v_sub_f32_e32 v185, v185, v154
	v_sub_f32_e32 v186, v186, v154
	v_sub_f32_e32 v187, v187, v154
	v_sub_f32_e32 v188, v188, v154
	v_sub_f32_e32 v189, v189, v154
	v_sub_f32_e32 v190, v190, v154
	v_sub_f32_e32 v191, v191, v154
	v_sub_f32_e32 v192, v192, v154
	v_sub_f32_e32 v193, v193, v154
	v_sub_f32_e32 v194, v194, v154
	v_sub_f32_e32 v195, v195, v154
	v_sub_f32_e32 v196, v196, v154
	v_sub_f32_e32 v197, v197, v154
	v_sub_f32_e32 v153, 0, v154
	v_exp_f32_e32 v154, v153
	s_nop 0
	v_mul_f32_e32 v179, v179, v154
	v_pk_mul_f32 v[48:49], v[48:49], v[154:155] op_sel_hi:[1,0]
	v_pk_mul_f32 v[50:51], v[50:51], v[154:155] op_sel_hi:[1,0]
	v_pk_mul_f32 v[52:53], v[52:53], v[154:155] op_sel_hi:[1,0]
	v_pk_mul_f32 v[54:55], v[54:55], v[154:155] op_sel_hi:[1,0]
	v_pk_mul_f32 v[56:57], v[56:57], v[154:155] op_sel_hi:[1,0]
	v_pk_mul_f32 v[58:59], v[58:59], v[154:155] op_sel_hi:[1,0]
	v_pk_mul_f32 v[60:61], v[60:61], v[154:155] op_sel_hi:[1,0]
	v_pk_mul_f32 v[62:63], v[62:63], v[154:155] op_sel_hi:[1,0]
	v_pk_mul_f32 v[32:33], v[32:33], v[154:155] op_sel_hi:[1,0]
	v_pk_mul_f32 v[34:35], v[34:35], v[154:155] op_sel_hi:[1,0]
	v_pk_mul_f32 v[36:37], v[36:37], v[154:155] op_sel_hi:[1,0]
	v_pk_mul_f32 v[38:39], v[38:39], v[154:155] op_sel_hi:[1,0]
	v_pk_mul_f32 v[40:41], v[40:41], v[154:155] op_sel_hi:[1,0]
	v_pk_mul_f32 v[42:43], v[42:43], v[154:155] op_sel_hi:[1,0]
	v_pk_mul_f32 v[44:45], v[44:45], v[154:155] op_sel_hi:[1,0]
	v_pk_mul_f32 v[46:47], v[46:47], v[154:155] op_sel_hi:[1,0]
	v_cndmask_b32_e64 v174, 0, v150, s[4:5]
	v_sub_f32_e32 v158, v158, v174
	v_sub_f32_e32 v159, v159, v174
	v_sub_f32_e32 v160, v160, v174
	v_sub_f32_e32 v161, v161, v174
	v_sub_f32_e32 v162, v162, v174
	v_sub_f32_e32 v163, v163, v174
	v_sub_f32_e32 v164, v164, v174
	v_sub_f32_e32 v165, v165, v174
	v_sub_f32_e32 v166, v166, v174
	v_sub_f32_e32 v167, v167, v174
	v_sub_f32_e32 v168, v168, v174
	v_sub_f32_e32 v169, v169, v174
	v_sub_f32_e32 v170, v170, v174
	v_sub_f32_e32 v171, v171, v174
	v_sub_f32_e32 v172, v172, v174
	v_sub_f32_e32 v173, v173, v174
	v_sub_f32_e32 v120, v120, v174
	v_sub_f32_e32 v121, v121, v174
	v_sub_f32_e32 v122, v122, v174
	v_sub_f32_e32 v123, v123, v174
	v_sub_f32_e32 v124, v124, v174
	v_sub_f32_e32 v125, v125, v174
	v_sub_f32_e32 v126, v126, v174
	v_sub_f32_e32 v127, v127, v174
	v_sub_f32_e32 v128, v128, v174
	v_sub_f32_e32 v129, v129, v174
	v_sub_f32_e32 v130, v130, v174
	v_sub_f32_e32 v131, v131, v174
	v_sub_f32_e32 v132, v132, v174
	v_sub_f32_e32 v133, v133, v174
	v_sub_f32_e32 v134, v134, v174
	v_sub_f32_e32 v135, v135, v174
	v_sub_f32_e32 v151, 0, v174
	v_exp_f32_e32 v174, v151
	s_nop 0
	v_mul_f32_e32 v178, v178, v174
	v_pk_mul_f32 v[16:17], v[16:17], v[174:175] op_sel_hi:[1,0]
	v_pk_mul_f32 v[18:19], v[18:19], v[174:175] op_sel_hi:[1,0]
	v_pk_mul_f32 v[20:21], v[20:21], v[174:175] op_sel_hi:[1,0]
	v_pk_mul_f32 v[22:23], v[22:23], v[174:175] op_sel_hi:[1,0]
	v_pk_mul_f32 v[24:25], v[24:25], v[174:175] op_sel_hi:[1,0]
	v_pk_mul_f32 v[26:27], v[26:27], v[174:175] op_sel_hi:[1,0]
	v_pk_mul_f32 v[28:29], v[28:29], v[174:175] op_sel_hi:[1,0]
	v_pk_mul_f32 v[30:31], v[30:31], v[174:175] op_sel_hi:[1,0]
	v_pk_mul_f32 v[0:1], v[0:1], v[174:175] op_sel_hi:[1,0]
	v_pk_mul_f32 v[2:3], v[2:3], v[174:175] op_sel_hi:[1,0]
	v_pk_mul_f32 v[4:5], v[4:5], v[174:175] op_sel_hi:[1,0]
	v_pk_mul_f32 v[6:7], v[6:7], v[174:175] op_sel_hi:[1,0]
	v_pk_mul_f32 v[8:9], v[8:9], v[174:175] op_sel_hi:[1,0]
	v_pk_mul_f32 v[10:11], v[10:11], v[174:175] op_sel_hi:[1,0]
	v_pk_mul_f32 v[12:13], v[12:13], v[174:175] op_sel_hi:[1,0]
	v_pk_mul_f32 v[14:15], v[14:15], v[174:175] op_sel_hi:[1,0]
; #define LAS __attribute__((address_space(3)))
; __device__ __forceinline__ unsigned pk2n(float lo, float hi) { const f32x2v v = {lo, hi}; const bf16v2 b = __builtin_convertvector(v, bf16v2); return __builtin_bit_cast(unsigned, b); }
; __device__ __forceinline__ float fexp2(float x) { return __builtin_amdgcn_exp2f(x); }
; template <bool KLDS>
; __device__ __forceinline__ void attn_step(const bf16x8 (&kf)[4], LAS const unsigned char* kb, const bf16x8 (&vf)[2][2], const bf16x8 (&qf)[4], f32x16& o0, f32x16& o1, float& m, float& l, int lane, int maskmode) {
;     ...
;     const float mn = fmaxf(m, tm), al = fexp2(m - mn); m = mn;
;     float ps = 0.f;
; #pragma unroll
;     for (int i = 0; i < 16; ++i) { S[i] = fexp2(S[i] - mn); ps += S[i]; }
;     l = l * al + ps;
; #pragma unroll
;     for (int i = 0; i < 16; ++i) { o0[i] *= al; o1[i] *= al; }
;     bf16x8 pf[2];
; #pragma unroll
;     for (int s2 = 0; s2 < 2; ++s2) {
;         u32x4 w; w.x = pk2n(S[8 * s2 + 0], S[8 * s2 + 1]); w.y = pk2n(S[8 * s2 + 2], S[8 * s2 + 3]); w.z = pk2n(S[8 * s2 + 4], S[8 * s2 + 5]); w.w = pk2n(S[8 * s2 + 6], S[8 * s2 + 7]);
;         pf[s2] = __builtin_bit_cast(bf16x8, w);
;     }
; #pragma unroll
;     for (int s2 = 0; s2 < 2; ++s2) {
;         o0 = __builtin_amdgcn_mfma_f32_32x32x16_bf16(vf[s2][0], pf[s2], o0, 0, 0, 0);
;         o1 = __builtin_amdgcn_mfma_f32_32x32x16_bf16(vf[s2][1], pf[s2], o1, 0, 0, 0);
;     }
; __device__ __forceinline__ void attnC_unit(const Args& a, int unit, LAS unsigned char* lds) {
;     ...
;     for (int kt = 0; kt < 32; ++kt) {
;         LAS unsigned char* cur = lds + (kt & 1) * 16384;
;         LAS unsigned char* nxt = lds + ((kt + 1) & 1) * 16384;
;         if (kt + 1 < 32) { *(LAS u32x4*)(nxt + kwo) = rk; *(LAS u32x4*)(nxt + vwo) = rv; }
;         if (kt + 2 < 32) { rk = *(const u32x4*)(kg + (size_t)(kt + 2) * TSTEP); rv = *(const u32x4*)(vg + (size_t)(kt + 2) * TSTEP); }
; #pragma unroll
;         for (int j = 0; j < 2; ++j) {
;             bf16x8 kf[4], vf[2][2];
;             load_kf(cur + j * 4096, kf, lane); load_vf(cur + 8192 + j * 4096, vf, lane);
; #pragma unroll
;             for (int e = 0; e < 2; ++e) attn_step<false>(kf, cur, vf, qf[e], o0[e], o1[e], m[e], l[e], lane, 0);
;         }
;         __syncthreads();
.LaN_fj1:
	v_exp_f32_e32 v64, v64
	v_exp_f32_e32 v158, v158
	v_exp_f32_e32 v65, v65
	v_exp_f32_e32 v159, v159
	v_exp_f32_e32 v66, v66
	v_exp_f32_e32 v160, v160
	v_add_f32_e32 v138, v64, v65
	v_add_f32_e32 v140, v158, v159
	v_exp_f32_e32 v67, v67
	v_exp_f32_e32 v161, v161
	v_add_f32_e32 v139, v66, v67
	v_add_f32_e32 v141, v160, v161
	v_exp_f32_e32 v68, v68
	v_exp_f32_e32 v162, v162
	v_exp_f32_e32 v69, v69
	v_exp_f32_e32 v163, v163
	v_add_f32_e32 v139, v139, v68
	v_add_f32_e32 v141, v141, v162
	v_exp_f32_e32 v70, v70
	v_exp_f32_e32 v164, v164
	v_add_f32_e32 v138, v138, v69
	v_add_f32_e32 v140, v140, v163
	v_exp_f32_e32 v71, v71
	v_exp_f32_e32 v165, v165
	v_add_f32_e32 v139, v139, v70
	v_add_f32_e32 v141, v141, v164
	v_exp_f32_e32 v72, v72
	v_exp_f32_e32 v166, v166
	v_add_f32_e32 v138, v138, v71
	v_add_f32_e32 v140, v140, v165
	v_exp_f32_e32 v73, v73
	v_exp_f32_e32 v167, v167
	v_add_f32_e32 v139, v139, v72
	v_add_f32_e32 v141, v141, v166
	v_exp_f32_e32 v74, v74
	v_exp_f32_e32 v168, v168
	v_add_f32_e32 v138, v138, v73
	v_add_f32_e32 v140, v140, v167
	v_exp_f32_e32 v75, v75
	v_exp_f32_e32 v169, v169
	v_add_f32_e32 v139, v139, v74
	v_add_f32_e32 v141, v141, v168
	v_exp_f32_e32 v76, v76
	v_exp_f32_e32 v170, v170
	v_add_f32_e32 v138, v138, v75
	v_add_f32_e32 v140, v140, v169
	v_exp_f32_e32 v77, v77
	v_exp_f32_e32 v171, v171
	v_add_f32_e32 v139, v139, v76
	v_add_f32_e32 v141, v141, v170
	v_exp_f32_e32 v78, v78
	v_exp_f32_e32 v172, v172
	v_add_f32_e32 v138, v138, v77
	v_add_f32_e32 v140, v140, v171
	v_exp_f32_e32 v79, v79
	v_exp_f32_e32 v173, v173
	v_add_f32_e32 v139, v139, v78
	v_add_f32_e32 v141, v141, v172
	s_nop 0
	s_nop 0
	v_add_f32_e32 v139, v139, v79
	v_add_f32_e32 v141, v141, v173
	v_add_f32_e32 v138, v138, v139
	v_add_f32_e32 v140, v140, v141
	v_add_f32_e32 v179, v179, v138
	v_add_f32_e32 v178, v178, v140
	v_cvt_pk_bf16_f32 v64, v64, v65
	v_cvt_pk_bf16_f32 v158, v158, v159
	v_cvt_pk_bf16_f32 v65, v66, v67
	v_cvt_pk_bf16_f32 v159, v160, v161
	v_cvt_pk_bf16_f32 v66, v68, v69
	v_cvt_pk_bf16_f32 v160, v162, v163
	v_cvt_pk_bf16_f32 v67, v70, v71
	v_cvt_pk_bf16_f32 v161, v164, v165
	v_cvt_pk_bf16_f32 v68, v72, v73
	v_cvt_pk_bf16_f32 v162, v166, v167
	v_cvt_pk_bf16_f32 v69, v74, v75
	v_cvt_pk_bf16_f32 v163, v168, v169
	v_cvt_pk_bf16_f32 v70, v76, v77
	v_cvt_pk_bf16_f32 v164, v170, v171
	v_cvt_pk_bf16_f32 v71, v78, v79
	v_cvt_pk_bf16_f32 v165, v172, v173
	s_waitcnt lgkmcnt(0)
	v_mfma_f32_32x32x16_bf16 v[48:63], v[146:149], v[64:67], v[48:63]
	v_mfma_f32_32x32x16_bf16 v[16:31], v[146:149], v[158:161], v[16:31]
	v_mfma_f32_32x32x16_bf16 v[32:47], v[204:207], v[64:67], v[32:47]
	v_mfma_f32_32x32x16_bf16 v[0:15], v[204:207], v[158:161], v[0:15]
	v_mfma_f32_32x32x16_bf16 v[48:63], v[208:211], v[68:71], v[48:63]
	v_mfma_f32_32x32x16_bf16 v[16:31], v[208:211], v[162:165], v[16:31]
	v_mfma_f32_32x32x16_bf16 v[32:47], v[212:215], v[68:71], v[32:47]
	v_mfma_f32_32x32x16_bf16 v[0:15], v[212:215], v[162:165], v[0:15]
	s_mov_b32 s33, s29
	s_mov_b32 s29, s30
	s_mov_b32 s30, s31
	s_mov_b32 s31, s33
	s_add_i32 s3, s3, 1
	s_cmp_lg_u32 s3, 32
	s_cbranch_scc1 .LaN_loop
	s_nop 15
	s_nop 7
	s_branch .LBB0_252
